# EpiRes epilogues (phases 7,10,14,17): the 4 residual quad loads of a row issued together into free VGPRs, wait vmcnt(3) instead of a vmcnt(0) after each of 32 loads
# speedup vs baseline: 1.0019x; 1.0019x over previous
.LBB0_946:
	v_lshlrev_b64 v[166:167], 2, v[166:167]
	v_lshl_add_u64 v[168:169], v[168:169], 0, v[166:167]
	global_load_dwordx4 v[234:237], v[168:169], off
	global_load_dwordx4 v[238:241], v[168:169], off offset:16
	global_load_dwordx4 v[242:245], v[168:169], off offset:512
	global_load_dwordx4 v[246:249], v[168:169], off offset:528
	v_lshl_add_u64 v[170:171], s[88:89], 0, v[170:171]
	v_lshl_add_u64 v[170:171], v[170:171], 0, v[166:167]
	s_andn2_b64 vcc, exec, s[42:43]
	s_waitcnt vmcnt(3)
	v_pk_mul_f32 v[236:237], v[236:237], s[16:17] op_sel_hi:[1,0]
	v_pk_mul_f32 v[234:235], v[234:235], s[16:17] op_sel_hi:[1,0]
	v_pk_fma_f32 v[144:145], v[144:145], v[124:125], v[236:237]
	v_pk_fma_f32 v[142:143], v[142:143], v[122:123], v[234:235]
	global_store_dwordx4 v[170:171], v[142:145], off
	s_nop 0
	s_waitcnt vmcnt(3)
	v_pk_mul_f32 v[240:241], v[240:241], s[16:17] op_sel_hi:[1,0]
	v_pk_mul_f32 v[238:239], v[238:239], s[16:17] op_sel_hi:[1,0]
	v_pk_fma_f32 v[140:141], v[140:141], v[116:117], v[240:241]
	v_pk_fma_f32 v[138:139], v[138:139], v[114:115], v[238:239]
	global_store_dwordx4 v[170:171], v[138:141], off offset:16
	s_nop 0
	s_waitcnt vmcnt(3)
	v_pk_mul_f32 v[244:245], v[244:245], s[16:17] op_sel_hi:[1,0]
	v_pk_mul_f32 v[242:243], v[242:243], s[16:17] op_sel_hi:[1,0]
	v_pk_fma_f32 v[136:137], v[136:137], v[112:113], v[244:245]
	v_pk_fma_f32 v[134:135], v[134:135], v[110:111], v[242:243]
	global_store_dwordx4 v[170:171], v[134:137], off offset:512
	s_nop 0
	s_waitcnt vmcnt(3)
	v_pk_mul_f32 v[248:249], v[248:249], s[16:17] op_sel_hi:[1,0]
	v_cndmask_b32_e64 v135, 0, 1, s[42:43]
	v_pk_mul_f32 v[246:247], v[246:247], s[16:17] op_sel_hi:[1,0]
	v_or_b32_e32 v134, 16, v164
	v_cmp_ne_u32_e64 s[4:5], 1, v135
	v_pk_fma_f32 v[130:131], v[130:131], v[102:103], v[246:247]
	v_pk_fma_f32 v[132:133], v[132:133], v[104:105], v[248:249]
	s_mov_b64 s[42:43], -1
	global_store_dwordx4 v[170:171], v[130:133], off offset:528
	s_cbranch_vccnz .LBB0_948
	v_ashrrev_i32_e32 v135, 31, v134
	v_lshlrev_b64 v[132:133], 12, v[134:135]
	v_lshl_add_u64 v[130:131], s[52:53], 0, v[132:133]
	s_mov_b64 s[42:43], 0

.LBB0_950:
	v_lshl_add_u64 v[130:131], v[130:131], 0, v[166:167]
	global_load_dwordx4 v[234:237], v[130:131], off
	global_load_dwordx4 v[238:241], v[130:131], off offset:16
	global_load_dwordx4 v[242:245], v[130:131], off offset:512
	global_load_dwordx4 v[246:249], v[130:131], off offset:528
	v_lshl_add_u64 v[132:133], s[88:89], 0, v[132:133]
	v_lshl_add_u64 v[132:133], v[132:133], 0, v[166:167]
	s_and_b64 vcc, exec, s[4:5]
	s_mov_b64 s[42:43], -1
	s_waitcnt vmcnt(3)
	v_pk_mul_f32 v[236:237], v[236:237], s[16:17] op_sel_hi:[1,0]
	v_pk_mul_f32 v[234:235], v[234:235], s[16:17] op_sel_hi:[1,0]
	v_pk_fma_f32 v[128:129], v[128:129], v[124:125], v[236:237]
	v_pk_fma_f32 v[126:127], v[126:127], v[122:123], v[234:235]
	global_store_dwordx4 v[132:133], v[126:129], off
	s_nop 0
	s_waitcnt vmcnt(3)
	v_pk_mul_f32 v[240:241], v[240:241], s[16:17] op_sel_hi:[1,0]
	v_pk_mul_f32 v[238:239], v[238:239], s[16:17] op_sel_hi:[1,0]
	v_pk_fma_f32 v[120:121], v[120:121], v[116:117], v[240:241]
	v_pk_fma_f32 v[118:119], v[118:119], v[114:115], v[238:239]
	global_store_dwordx4 v[132:133], v[118:121], off offset:16
	s_nop 0
	s_waitcnt vmcnt(3)
	v_pk_mul_f32 v[244:245], v[244:245], s[16:17] op_sel_hi:[1,0]
	v_pk_mul_f32 v[242:243], v[242:243], s[16:17] op_sel_hi:[1,0]
	v_pk_fma_f32 v[108:109], v[108:109], v[112:113], v[244:245]
	v_pk_fma_f32 v[106:107], v[106:107], v[110:111], v[242:243]
	global_store_dwordx4 v[132:133], v[106:109], off offset:512
	s_nop 0
	s_waitcnt vmcnt(3)
	v_pk_mul_f32 v[246:247], v[246:247], s[16:17] op_sel_hi:[1,0]
	v_pk_mul_f32 v[108:109], v[248:249], s[16:17] op_sel_hi:[1,0]
	v_or_b32_e32 v106, 32, v164
	v_pk_fma_f32 v[98:99], v[98:99], v[102:103], v[246:247]
	v_pk_fma_f32 v[100:101], v[100:101], v[104:105], v[108:109]
	global_store_dwordx4 v[132:133], v[98:101], off offset:528
	s_cbranch_vccnz .LBB0_952
	v_ashrrev_i32_e32 v107, 31, v106
	v_lshlrev_b64 v[100:101], 12, v[106:107]
	v_lshl_add_u64 v[98:99], s[52:53], 0, v[100:101]
	s_mov_b64 s[42:43], 0

.LBB0_954:
	v_lshl_add_u64 v[98:99], v[98:99], 0, v[166:167]
	global_load_dwordx4 v[234:237], v[98:99], off
	global_load_dwordx4 v[238:241], v[98:99], off offset:16
	global_load_dwordx4 v[242:245], v[98:99], off offset:512
	global_load_dwordx4 v[246:249], v[98:99], off offset:528
	v_lshl_add_u64 v[100:101], s[88:89], 0, v[100:101]
	v_lshl_add_u64 v[100:101], v[100:101], 0, v[166:167]
	s_and_b64 vcc, exec, s[4:5]
	s_mov_b64 s[42:43], -1
	s_waitcnt vmcnt(3)
	v_pk_mul_f32 v[236:237], v[236:237], s[16:17] op_sel_hi:[1,0]
	v_pk_mul_f32 v[234:235], v[234:235], s[16:17] op_sel_hi:[1,0]
	v_pk_fma_f32 v[96:97], v[96:97], v[124:125], v[236:237]
	v_pk_fma_f32 v[94:95], v[94:95], v[122:123], v[234:235]
	global_store_dwordx4 v[100:101], v[94:97], off
	s_nop 0
	s_waitcnt vmcnt(3)
	v_pk_mul_f32 v[240:241], v[240:241], s[16:17] op_sel_hi:[1,0]
	v_pk_mul_f32 v[238:239], v[238:239], s[16:17] op_sel_hi:[1,0]
	v_pk_fma_f32 v[92:93], v[92:93], v[116:117], v[240:241]
	v_pk_fma_f32 v[90:91], v[90:91], v[114:115], v[238:239]
	global_store_dwordx4 v[100:101], v[90:93], off offset:16
	s_nop 0
	s_waitcnt vmcnt(3)
	v_pk_mul_f32 v[244:245], v[244:245], s[16:17] op_sel_hi:[1,0]
	v_pk_mul_f32 v[242:243], v[242:243], s[16:17] op_sel_hi:[1,0]
	v_pk_fma_f32 v[88:89], v[88:89], v[112:113], v[244:245]
	v_pk_fma_f32 v[86:87], v[86:87], v[110:111], v[242:243]
	global_store_dwordx4 v[100:101], v[86:89], off offset:512
	s_nop 0
	s_waitcnt vmcnt(3)
	v_pk_mul_f32 v[248:249], v[248:249], s[16:17] op_sel_hi:[1,0]
	v_pk_mul_f32 v[246:247], v[246:247], s[16:17] op_sel_hi:[1,0]
	v_or_b32_e32 v86, 48, v164
	v_pk_fma_f32 v[82:83], v[82:83], v[102:103], v[246:247]
	v_pk_fma_f32 v[84:85], v[84:85], v[104:105], v[248:249]
	global_store_dwordx4 v[100:101], v[82:85], off offset:528
	s_cbranch_vccnz .LBB0_956
	v_ashrrev_i32_e32 v87, 31, v86
	v_lshlrev_b64 v[84:85], 12, v[86:87]
	v_lshl_add_u64 v[82:83], s[52:53], 0, v[84:85]
	s_mov_b64 s[42:43], 0

.LBB0_958:
	v_lshl_add_u64 v[82:83], v[82:83], 0, v[166:167]
	global_load_dwordx4 v[234:237], v[82:83], off
	global_load_dwordx4 v[238:241], v[82:83], off offset:16
	global_load_dwordx4 v[242:245], v[82:83], off offset:512
	global_load_dwordx4 v[246:249], v[82:83], off offset:528
	v_lshl_add_u64 v[84:85], s[88:89], 0, v[84:85]
	v_lshl_add_u64 v[84:85], v[84:85], 0, v[166:167]
	s_and_b64 vcc, exec, s[4:5]
	s_mov_b64 s[42:43], -1
	s_waitcnt vmcnt(3)
	v_pk_mul_f32 v[236:237], v[236:237], s[16:17] op_sel_hi:[1,0]
	v_pk_mul_f32 v[234:235], v[234:235], s[16:17] op_sel_hi:[1,0]
	v_pk_fma_f32 v[80:81], v[80:81], v[124:125], v[236:237]
	v_pk_fma_f32 v[78:79], v[78:79], v[122:123], v[234:235]
	global_store_dwordx4 v[84:85], v[78:81], off
	s_nop 0
	s_waitcnt vmcnt(3)
	v_pk_mul_f32 v[240:241], v[240:241], s[16:17] op_sel_hi:[1,0]
	v_pk_mul_f32 v[238:239], v[238:239], s[16:17] op_sel_hi:[1,0]
	v_pk_fma_f32 v[76:77], v[76:77], v[116:117], v[240:241]
	v_pk_fma_f32 v[74:75], v[74:75], v[114:115], v[238:239]
	global_store_dwordx4 v[84:85], v[74:77], off offset:16
	s_nop 0
	s_waitcnt vmcnt(3)
	v_pk_mul_f32 v[244:245], v[244:245], s[16:17] op_sel_hi:[1,0]
	v_pk_mul_f32 v[242:243], v[242:243], s[16:17] op_sel_hi:[1,0]
	v_pk_fma_f32 v[72:73], v[72:73], v[112:113], v[244:245]
	v_pk_fma_f32 v[70:71], v[70:71], v[110:111], v[242:243]
	global_store_dwordx4 v[84:85], v[70:73], off offset:512
	s_nop 0
	s_waitcnt vmcnt(3)
	v_pk_mul_f32 v[248:249], v[248:249], s[16:17] op_sel_hi:[1,0]
	v_pk_mul_f32 v[246:247], v[246:247], s[16:17] op_sel_hi:[1,0]
	v_add_u32_e32 v70, 0x80, v164
	v_pk_fma_f32 v[66:67], v[66:67], v[102:103], v[246:247]
	v_pk_fma_f32 v[68:69], v[68:69], v[104:105], v[248:249]
	global_store_dwordx4 v[84:85], v[66:69], off offset:528
	s_cbranch_vccnz .LBB0_960
	v_ashrrev_i32_e32 v71, 31, v70
	v_lshlrev_b64 v[68:69], 12, v[70:71]
	v_lshl_add_u64 v[66:67], s[52:53], 0, v[68:69]
	s_mov_b64 s[42:43], 0

.LBB0_962:
	v_lshl_add_u64 v[66:67], v[66:67], 0, v[166:167]
	global_load_dwordx4 v[234:237], v[66:67], off
	global_load_dwordx4 v[238:241], v[66:67], off offset:16
	global_load_dwordx4 v[242:245], v[66:67], off offset:512
	global_load_dwordx4 v[246:249], v[66:67], off offset:528
	v_lshl_add_u64 v[68:69], s[88:89], 0, v[68:69]
	v_lshl_add_u64 v[68:69], v[68:69], 0, v[166:167]
	s_and_b64 vcc, exec, s[4:5]
	s_mov_b64 s[42:43], -1
	s_waitcnt vmcnt(3)
	v_pk_mul_f32 v[236:237], v[236:237], s[16:17] op_sel_hi:[1,0]
	v_pk_mul_f32 v[234:235], v[234:235], s[16:17] op_sel_hi:[1,0]
	v_pk_fma_f32 v[64:65], v[64:65], v[124:125], v[236:237]
	v_pk_fma_f32 v[62:63], v[62:63], v[122:123], v[234:235]
	global_store_dwordx4 v[68:69], v[62:65], off
	s_nop 0
	s_waitcnt vmcnt(3)
	v_pk_mul_f32 v[240:241], v[240:241], s[16:17] op_sel_hi:[1,0]
	v_pk_mul_f32 v[238:239], v[238:239], s[16:17] op_sel_hi:[1,0]
	v_pk_fma_f32 v[60:61], v[60:61], v[116:117], v[240:241]
	v_pk_fma_f32 v[58:59], v[58:59], v[114:115], v[238:239]
	global_store_dwordx4 v[68:69], v[58:61], off offset:16
	s_nop 0
	s_waitcnt vmcnt(3)
	v_pk_mul_f32 v[244:245], v[244:245], s[16:17] op_sel_hi:[1,0]
	v_pk_mul_f32 v[242:243], v[242:243], s[16:17] op_sel_hi:[1,0]
	v_pk_fma_f32 v[56:57], v[56:57], v[112:113], v[244:245]
	v_pk_fma_f32 v[54:55], v[54:55], v[110:111], v[242:243]
	global_store_dwordx4 v[68:69], v[54:57], off offset:512
	s_nop 0
	s_waitcnt vmcnt(3)
	v_pk_mul_f32 v[248:249], v[248:249], s[16:17] op_sel_hi:[1,0]
	v_pk_mul_f32 v[246:247], v[246:247], s[16:17] op_sel_hi:[1,0]
	v_add_u32_e32 v54, 0x90, v164
	v_pk_fma_f32 v[50:51], v[50:51], v[102:103], v[246:247]
	v_pk_fma_f32 v[52:53], v[52:53], v[104:105], v[248:249]
	global_store_dwordx4 v[68:69], v[50:53], off offset:528
	s_cbranch_vccnz .LBB0_964
	v_ashrrev_i32_e32 v55, 31, v54
	v_lshlrev_b64 v[52:53], 12, v[54:55]
	v_lshl_add_u64 v[50:51], s[52:53], 0, v[52:53]
	s_mov_b64 s[42:43], 0

.LBB0_966:
	v_lshl_add_u64 v[50:51], v[50:51], 0, v[166:167]
	global_load_dwordx4 v[234:237], v[50:51], off
	global_load_dwordx4 v[238:241], v[50:51], off offset:16
	global_load_dwordx4 v[242:245], v[50:51], off offset:512
	global_load_dwordx4 v[246:249], v[50:51], off offset:528
	v_lshl_add_u64 v[52:53], s[88:89], 0, v[52:53]
	v_lshl_add_u64 v[52:53], v[52:53], 0, v[166:167]
	s_and_b64 vcc, exec, s[4:5]
	s_mov_b64 s[42:43], -1
	s_waitcnt vmcnt(3)
	v_pk_mul_f32 v[236:237], v[236:237], s[16:17] op_sel_hi:[1,0]
	v_pk_mul_f32 v[234:235], v[234:235], s[16:17] op_sel_hi:[1,0]
	v_pk_fma_f32 v[48:49], v[48:49], v[124:125], v[236:237]
	v_pk_fma_f32 v[46:47], v[46:47], v[122:123], v[234:235]
	global_store_dwordx4 v[52:53], v[46:49], off
	s_nop 0
	s_waitcnt vmcnt(3)
	v_pk_mul_f32 v[240:241], v[240:241], s[16:17] op_sel_hi:[1,0]
	v_pk_mul_f32 v[238:239], v[238:239], s[16:17] op_sel_hi:[1,0]
	v_pk_fma_f32 v[44:45], v[44:45], v[116:117], v[240:241]
	v_pk_fma_f32 v[42:43], v[42:43], v[114:115], v[238:239]
	global_store_dwordx4 v[52:53], v[42:45], off offset:16
	s_nop 0
	s_waitcnt vmcnt(3)
	v_pk_mul_f32 v[244:245], v[244:245], s[16:17] op_sel_hi:[1,0]
	v_pk_mul_f32 v[242:243], v[242:243], s[16:17] op_sel_hi:[1,0]
	v_pk_fma_f32 v[40:41], v[40:41], v[112:113], v[244:245]
	v_pk_fma_f32 v[38:39], v[38:39], v[110:111], v[242:243]
	global_store_dwordx4 v[52:53], v[38:41], off offset:512
	s_nop 0
	s_waitcnt vmcnt(3)
	v_pk_mul_f32 v[248:249], v[248:249], s[16:17] op_sel_hi:[1,0]
	v_pk_mul_f32 v[246:247], v[246:247], s[16:17] op_sel_hi:[1,0]
	v_add_u32_e32 v38, 0xa0, v164
	v_pk_fma_f32 v[34:35], v[34:35], v[102:103], v[246:247]
	v_pk_fma_f32 v[36:37], v[36:37], v[104:105], v[248:249]
	global_store_dwordx4 v[52:53], v[34:37], off offset:528
	s_cbranch_vccnz .LBB0_968
	v_ashrrev_i32_e32 v39, 31, v38
	v_lshlrev_b64 v[36:37], 12, v[38:39]
	v_lshl_add_u64 v[34:35], s[52:53], 0, v[36:37]
	s_mov_b64 s[42:43], 0

.LBB0_970:
	v_lshl_add_u64 v[34:35], v[34:35], 0, v[166:167]
	global_load_dwordx4 v[234:237], v[34:35], off
	global_load_dwordx4 v[238:241], v[34:35], off offset:16
	global_load_dwordx4 v[242:245], v[34:35], off offset:512
	global_load_dwordx4 v[246:249], v[34:35], off offset:528
	v_lshl_add_u64 v[36:37], s[88:89], 0, v[36:37]
	v_lshl_add_u64 v[36:37], v[36:37], 0, v[166:167]
	s_and_b64 vcc, exec, s[4:5]
	s_mov_b64 s[4:5], -1
	s_waitcnt vmcnt(3)
	v_pk_mul_f32 v[236:237], v[236:237], s[16:17] op_sel_hi:[1,0]
	v_pk_mul_f32 v[234:235], v[234:235], s[16:17] op_sel_hi:[1,0]
	v_pk_fma_f32 v[32:33], v[32:33], v[124:125], v[236:237]
	v_pk_fma_f32 v[30:31], v[30:31], v[122:123], v[234:235]
	global_store_dwordx4 v[36:37], v[30:33], off
	s_nop 0
	s_waitcnt vmcnt(3)
	v_pk_mul_f32 v[240:241], v[240:241], s[16:17] op_sel_hi:[1,0]
	v_pk_mul_f32 v[238:239], v[238:239], s[16:17] op_sel_hi:[1,0]
	v_pk_fma_f32 v[28:29], v[28:29], v[116:117], v[240:241]
	v_pk_fma_f32 v[26:27], v[26:27], v[114:115], v[238:239]
	global_store_dwordx4 v[36:37], v[26:29], off offset:16
	s_nop 0
	s_waitcnt vmcnt(3)
	v_pk_mul_f32 v[244:245], v[244:245], s[16:17] op_sel_hi:[1,0]
	v_pk_mul_f32 v[242:243], v[242:243], s[16:17] op_sel_hi:[1,0]
	v_pk_fma_f32 v[24:25], v[24:25], v[112:113], v[244:245]
	v_pk_fma_f32 v[22:23], v[22:23], v[110:111], v[242:243]
	global_store_dwordx4 v[36:37], v[22:25], off offset:512
	s_nop 0
	s_waitcnt vmcnt(3)
	v_pk_mul_f32 v[248:249], v[248:249], s[16:17] op_sel_hi:[1,0]
	v_pk_mul_f32 v[246:247], v[246:247], s[16:17] op_sel_hi:[1,0]
	v_add_u32_e32 v22, 0xb0, v164
	v_pk_fma_f32 v[18:19], v[18:19], v[102:103], v[246:247]
	v_pk_fma_f32 v[20:21], v[20:21], v[104:105], v[248:249]
	global_store_dwordx4 v[36:37], v[18:21], off offset:528
	s_cbranch_vccnz .LBB0_972
	v_ashrrev_i32_e32 v23, 31, v22
	v_lshlrev_b64 v[20:21], 12, v[22:23]
	v_lshl_add_u64 v[18:19], s[52:53], 0, v[20:21]
	s_mov_b64 s[4:5], 0

.LBB0_974:
	v_lshl_add_u64 v[18:19], v[18:19], 0, v[166:167]
	global_load_dwordx4 v[234:237], v[18:19], off
	global_load_dwordx4 v[238:241], v[18:19], off offset:16
	global_load_dwordx4 v[242:245], v[18:19], off offset:512
	global_load_dwordx4 v[246:249], v[18:19], off offset:528
	v_lshl_add_u64 v[20:21], s[88:89], 0, v[20:21]
	v_lshl_add_u64 v[20:21], v[20:21], 0, v[166:167]
	s_andn2_b64 vcc, exec, s[2:3]
	s_mov_b64 s[2:3], -1
	s_waitcnt vmcnt(3)
	v_pk_mul_f32 v[236:237], v[236:237], s[16:17] op_sel_hi:[1,0]
	v_pk_mul_f32 v[234:235], v[234:235], s[16:17] op_sel_hi:[1,0]
	v_pk_fma_f32 v[16:17], v[16:17], v[124:125], v[236:237]
	v_pk_fma_f32 v[14:15], v[14:15], v[122:123], v[234:235]
	global_store_dwordx4 v[20:21], v[14:17], off
	s_nop 0
	s_waitcnt vmcnt(3)
	v_pk_mul_f32 v[240:241], v[240:241], s[16:17] op_sel_hi:[1,0]
	v_pk_mul_f32 v[238:239], v[238:239], s[16:17] op_sel_hi:[1,0]
	v_pk_fma_f32 v[12:13], v[12:13], v[116:117], v[240:241]
	v_pk_fma_f32 v[10:11], v[10:11], v[114:115], v[238:239]
	global_store_dwordx4 v[20:21], v[10:13], off offset:16
	s_nop 0
	s_waitcnt vmcnt(3)
	v_pk_mul_f32 v[244:245], v[244:245], s[16:17] op_sel_hi:[1,0]
	v_pk_mul_f32 v[242:243], v[242:243], s[16:17] op_sel_hi:[1,0]
	v_pk_fma_f32 v[8:9], v[8:9], v[112:113], v[244:245]
	v_pk_fma_f32 v[6:7], v[6:7], v[110:111], v[242:243]
	global_store_dwordx4 v[20:21], v[6:9], off offset:512
	s_nop 0
	s_waitcnt vmcnt(3)
	v_pk_mul_f32 v[248:249], v[248:249], s[16:17] op_sel_hi:[1,0]
	v_pk_mul_f32 v[246:247], v[246:247], s[16:17] op_sel_hi:[1,0]
	v_pk_fma_f32 v[4:5], v[4:5], v[104:105], v[248:249]
	v_pk_fma_f32 v[2:3], v[2:3], v[102:103], v[246:247]
	global_store_dwordx4 v[20:21], v[2:5], off offset:528
	s_cbranch_vccnz .LBB0_931
	s_andn2_b64 vcc, exec, s[8:9]
	s_cbranch_vccnz .LBB0_930
	s_barrier
	s_branch .LBB0_930

.LBB0_1259:
	v_lshlrev_b64 v[166:167], 2, v[166:167]
	v_lshl_add_u64 v[168:169], v[168:169], 0, v[166:167]
	global_load_dwordx4 v[234:237], v[168:169], off
	global_load_dwordx4 v[238:241], v[168:169], off offset:16
	global_load_dwordx4 v[242:245], v[168:169], off offset:512
	global_load_dwordx4 v[246:249], v[168:169], off offset:528
	v_lshl_add_u64 v[170:171], s[88:89], 0, v[170:171]
	v_lshl_add_u64 v[170:171], v[170:171], 0, v[166:167]
	s_andn2_b64 vcc, exec, s[44:45]
	s_waitcnt vmcnt(3)
	v_pk_mul_f32 v[236:237], v[236:237], s[22:23] op_sel_hi:[1,0]
	v_pk_mul_f32 v[234:235], v[234:235], s[22:23] op_sel_hi:[1,0]
	v_pk_fma_f32 v[144:145], v[144:145], v[124:125], v[236:237]
	v_pk_fma_f32 v[142:143], v[142:143], v[122:123], v[234:235]
	global_store_dwordx4 v[170:171], v[142:145], off
	s_nop 0
	s_waitcnt vmcnt(3)
	v_pk_mul_f32 v[240:241], v[240:241], s[22:23] op_sel_hi:[1,0]
	v_pk_mul_f32 v[238:239], v[238:239], s[22:23] op_sel_hi:[1,0]
	v_pk_fma_f32 v[140:141], v[140:141], v[116:117], v[240:241]
	v_pk_fma_f32 v[138:139], v[138:139], v[114:115], v[238:239]
	global_store_dwordx4 v[170:171], v[138:141], off offset:16
	s_nop 0
	s_waitcnt vmcnt(3)
	v_pk_mul_f32 v[244:245], v[244:245], s[22:23] op_sel_hi:[1,0]
	v_pk_mul_f32 v[242:243], v[242:243], s[22:23] op_sel_hi:[1,0]
	v_pk_fma_f32 v[136:137], v[136:137], v[112:113], v[244:245]
	v_pk_fma_f32 v[134:135], v[134:135], v[110:111], v[242:243]
	global_store_dwordx4 v[170:171], v[134:137], off offset:512
	s_nop 0
	s_waitcnt vmcnt(3)
	v_pk_mul_f32 v[248:249], v[248:249], s[22:23] op_sel_hi:[1,0]
	v_cndmask_b32_e64 v135, 0, 1, s[44:45]
	v_pk_mul_f32 v[246:247], v[246:247], s[22:23] op_sel_hi:[1,0]
	v_or_b32_e32 v134, 16, v164
	v_cmp_ne_u32_e64 s[4:5], 1, v135
	v_pk_fma_f32 v[130:131], v[130:131], v[106:107], v[246:247]
	v_pk_fma_f32 v[132:133], v[132:133], v[108:109], v[248:249]
	s_mov_b64 s[44:45], -1
	global_store_dwordx4 v[170:171], v[130:133], off offset:528
	s_cbranch_vccnz .LBB0_1261
	v_ashrrev_i32_e32 v135, 31, v134
	v_lshlrev_b64 v[132:133], 12, v[134:135]
	v_lshl_add_u64 v[130:131], s[6:7], 0, v[132:133]
	s_mov_b64 s[44:45], 0

.LBB0_1263:
	v_lshl_add_u64 v[130:131], v[130:131], 0, v[166:167]
	global_load_dwordx4 v[234:237], v[130:131], off
	global_load_dwordx4 v[238:241], v[130:131], off offset:16
	global_load_dwordx4 v[242:245], v[130:131], off offset:512
	global_load_dwordx4 v[246:249], v[130:131], off offset:528
	v_lshl_add_u64 v[132:133], s[88:89], 0, v[132:133]
	v_lshl_add_u64 v[132:133], v[132:133], 0, v[166:167]
	s_and_b64 vcc, exec, s[4:5]
	s_mov_b64 s[44:45], -1
	s_waitcnt vmcnt(3)
	v_pk_mul_f32 v[236:237], v[236:237], s[22:23] op_sel_hi:[1,0]
	v_pk_mul_f32 v[234:235], v[234:235], s[22:23] op_sel_hi:[1,0]
	v_pk_fma_f32 v[128:129], v[128:129], v[124:125], v[236:237]
	v_pk_fma_f32 v[126:127], v[126:127], v[122:123], v[234:235]
	global_store_dwordx4 v[132:133], v[126:129], off
	s_nop 0
	s_waitcnt vmcnt(3)
	v_pk_mul_f32 v[240:241], v[240:241], s[22:23] op_sel_hi:[1,0]
	v_pk_mul_f32 v[238:239], v[238:239], s[22:23] op_sel_hi:[1,0]
	v_pk_fma_f32 v[120:121], v[120:121], v[116:117], v[240:241]
	v_pk_fma_f32 v[118:119], v[118:119], v[114:115], v[238:239]
	global_store_dwordx4 v[132:133], v[118:121], off offset:16
	s_nop 0
	s_waitcnt vmcnt(3)
	v_pk_mul_f32 v[244:245], v[244:245], s[22:23] op_sel_hi:[1,0]
	v_pk_mul_f32 v[242:243], v[242:243], s[22:23] op_sel_hi:[1,0]
	v_pk_fma_f32 v[104:105], v[104:105], v[112:113], v[244:245]
	v_pk_fma_f32 v[102:103], v[102:103], v[110:111], v[242:243]
	global_store_dwordx4 v[132:133], v[102:105], off offset:512
	s_nop 0
	s_waitcnt vmcnt(3)
	v_pk_mul_f32 v[246:247], v[246:247], s[22:23] op_sel_hi:[1,0]
	v_pk_mul_f32 v[104:105], v[248:249], s[22:23] op_sel_hi:[1,0]
	v_or_b32_e32 v102, 32, v164
	v_pk_fma_f32 v[98:99], v[98:99], v[106:107], v[246:247]
	v_pk_fma_f32 v[100:101], v[100:101], v[108:109], v[104:105]
	global_store_dwordx4 v[132:133], v[98:101], off offset:528
	s_cbranch_vccnz .LBB0_1265
	v_ashrrev_i32_e32 v103, 31, v102
	v_lshlrev_b64 v[100:101], 12, v[102:103]
	v_lshl_add_u64 v[98:99], s[6:7], 0, v[100:101]
	s_mov_b64 s[44:45], 0

.LBB0_1267:
	v_lshl_add_u64 v[98:99], v[98:99], 0, v[166:167]
	global_load_dwordx4 v[234:237], v[98:99], off
	global_load_dwordx4 v[238:241], v[98:99], off offset:16
	global_load_dwordx4 v[242:245], v[98:99], off offset:512
	global_load_dwordx4 v[246:249], v[98:99], off offset:528
	v_lshl_add_u64 v[100:101], s[88:89], 0, v[100:101]
	v_lshl_add_u64 v[100:101], v[100:101], 0, v[166:167]
	s_and_b64 vcc, exec, s[4:5]
	s_mov_b64 s[44:45], -1
	s_waitcnt vmcnt(3)
	v_pk_mul_f32 v[236:237], v[236:237], s[22:23] op_sel_hi:[1,0]
	v_pk_mul_f32 v[234:235], v[234:235], s[22:23] op_sel_hi:[1,0]
	v_pk_fma_f32 v[96:97], v[96:97], v[124:125], v[236:237]
	v_pk_fma_f32 v[94:95], v[94:95], v[122:123], v[234:235]
	global_store_dwordx4 v[100:101], v[94:97], off
	s_nop 0
	s_waitcnt vmcnt(3)
	v_pk_mul_f32 v[240:241], v[240:241], s[22:23] op_sel_hi:[1,0]
	v_pk_mul_f32 v[238:239], v[238:239], s[22:23] op_sel_hi:[1,0]
	v_pk_fma_f32 v[92:93], v[92:93], v[116:117], v[240:241]
	v_pk_fma_f32 v[90:91], v[90:91], v[114:115], v[238:239]
	global_store_dwordx4 v[100:101], v[90:93], off offset:16
	s_nop 0
	s_waitcnt vmcnt(3)
	v_pk_mul_f32 v[244:245], v[244:245], s[22:23] op_sel_hi:[1,0]
	v_pk_mul_f32 v[242:243], v[242:243], s[22:23] op_sel_hi:[1,0]
	v_pk_fma_f32 v[88:89], v[88:89], v[112:113], v[244:245]
	v_pk_fma_f32 v[86:87], v[86:87], v[110:111], v[242:243]
	global_store_dwordx4 v[100:101], v[86:89], off offset:512
	s_nop 0
	s_waitcnt vmcnt(3)
	v_pk_mul_f32 v[248:249], v[248:249], s[22:23] op_sel_hi:[1,0]
	v_pk_mul_f32 v[246:247], v[246:247], s[22:23] op_sel_hi:[1,0]
	v_or_b32_e32 v86, 48, v164
	v_pk_fma_f32 v[82:83], v[82:83], v[106:107], v[246:247]
	v_pk_fma_f32 v[84:85], v[84:85], v[108:109], v[248:249]
	global_store_dwordx4 v[100:101], v[82:85], off offset:528
	s_cbranch_vccnz .LBB0_1269
	v_ashrrev_i32_e32 v87, 31, v86
	v_lshlrev_b64 v[84:85], 12, v[86:87]
	v_lshl_add_u64 v[82:83], s[6:7], 0, v[84:85]
	s_mov_b64 s[44:45], 0

.LBB0_1271:
	v_lshl_add_u64 v[82:83], v[82:83], 0, v[166:167]
	global_load_dwordx4 v[234:237], v[82:83], off
	global_load_dwordx4 v[238:241], v[82:83], off offset:16
	global_load_dwordx4 v[242:245], v[82:83], off offset:512
	global_load_dwordx4 v[246:249], v[82:83], off offset:528
	v_lshl_add_u64 v[84:85], s[88:89], 0, v[84:85]
	v_lshl_add_u64 v[84:85], v[84:85], 0, v[166:167]
	s_and_b64 vcc, exec, s[4:5]
	s_mov_b64 s[44:45], -1
	s_waitcnt vmcnt(3)
	v_pk_mul_f32 v[236:237], v[236:237], s[22:23] op_sel_hi:[1,0]
	v_pk_mul_f32 v[234:235], v[234:235], s[22:23] op_sel_hi:[1,0]
	v_pk_fma_f32 v[80:81], v[80:81], v[124:125], v[236:237]
	v_pk_fma_f32 v[78:79], v[78:79], v[122:123], v[234:235]
	global_store_dwordx4 v[84:85], v[78:81], off
	s_nop 0
	s_waitcnt vmcnt(3)
	v_pk_mul_f32 v[240:241], v[240:241], s[22:23] op_sel_hi:[1,0]
	v_pk_mul_f32 v[238:239], v[238:239], s[22:23] op_sel_hi:[1,0]
	v_pk_fma_f32 v[76:77], v[76:77], v[116:117], v[240:241]
	v_pk_fma_f32 v[74:75], v[74:75], v[114:115], v[238:239]
	global_store_dwordx4 v[84:85], v[74:77], off offset:16
	s_nop 0
	s_waitcnt vmcnt(3)
	v_pk_mul_f32 v[244:245], v[244:245], s[22:23] op_sel_hi:[1,0]
	v_pk_mul_f32 v[242:243], v[242:243], s[22:23] op_sel_hi:[1,0]
	v_pk_fma_f32 v[72:73], v[72:73], v[112:113], v[244:245]
	v_pk_fma_f32 v[70:71], v[70:71], v[110:111], v[242:243]
	global_store_dwordx4 v[84:85], v[70:73], off offset:512
	s_nop 0
	s_waitcnt vmcnt(3)
	v_pk_mul_f32 v[248:249], v[248:249], s[22:23] op_sel_hi:[1,0]
	v_pk_mul_f32 v[246:247], v[246:247], s[22:23] op_sel_hi:[1,0]
	v_add_u32_e32 v70, 0x80, v164
	v_pk_fma_f32 v[66:67], v[66:67], v[106:107], v[246:247]
	v_pk_fma_f32 v[68:69], v[68:69], v[108:109], v[248:249]
	global_store_dwordx4 v[84:85], v[66:69], off offset:528
	s_cbranch_vccnz .LBB0_1273
	v_ashrrev_i32_e32 v71, 31, v70
	v_lshlrev_b64 v[68:69], 12, v[70:71]
	v_lshl_add_u64 v[66:67], s[6:7], 0, v[68:69]
	s_mov_b64 s[44:45], 0

.LBB0_1275:
	v_lshl_add_u64 v[66:67], v[66:67], 0, v[166:167]
	global_load_dwordx4 v[234:237], v[66:67], off
	global_load_dwordx4 v[238:241], v[66:67], off offset:16
	global_load_dwordx4 v[242:245], v[66:67], off offset:512
	global_load_dwordx4 v[246:249], v[66:67], off offset:528
	v_lshl_add_u64 v[68:69], s[88:89], 0, v[68:69]
	v_lshl_add_u64 v[68:69], v[68:69], 0, v[166:167]
	s_and_b64 vcc, exec, s[4:5]
	s_mov_b64 s[44:45], -1
	s_waitcnt vmcnt(3)
	v_pk_mul_f32 v[236:237], v[236:237], s[22:23] op_sel_hi:[1,0]
	v_pk_mul_f32 v[234:235], v[234:235], s[22:23] op_sel_hi:[1,0]
	v_pk_fma_f32 v[64:65], v[64:65], v[124:125], v[236:237]
	v_pk_fma_f32 v[62:63], v[62:63], v[122:123], v[234:235]
	global_store_dwordx4 v[68:69], v[62:65], off
	s_nop 0
	s_waitcnt vmcnt(3)
	v_pk_mul_f32 v[240:241], v[240:241], s[22:23] op_sel_hi:[1,0]
	v_pk_mul_f32 v[238:239], v[238:239], s[22:23] op_sel_hi:[1,0]
	v_pk_fma_f32 v[60:61], v[60:61], v[116:117], v[240:241]
	v_pk_fma_f32 v[58:59], v[58:59], v[114:115], v[238:239]
	global_store_dwordx4 v[68:69], v[58:61], off offset:16
	s_nop 0
	s_waitcnt vmcnt(3)
	v_pk_mul_f32 v[244:245], v[244:245], s[22:23] op_sel_hi:[1,0]
	v_pk_mul_f32 v[242:243], v[242:243], s[22:23] op_sel_hi:[1,0]
	v_pk_fma_f32 v[56:57], v[56:57], v[112:113], v[244:245]
	v_pk_fma_f32 v[54:55], v[54:55], v[110:111], v[242:243]
	global_store_dwordx4 v[68:69], v[54:57], off offset:512
	s_nop 0
	s_waitcnt vmcnt(3)
	v_pk_mul_f32 v[248:249], v[248:249], s[22:23] op_sel_hi:[1,0]
	v_pk_mul_f32 v[246:247], v[246:247], s[22:23] op_sel_hi:[1,0]
	v_add_u32_e32 v54, 0x90, v164
	v_pk_fma_f32 v[50:51], v[50:51], v[106:107], v[246:247]
	v_pk_fma_f32 v[52:53], v[52:53], v[108:109], v[248:249]
	global_store_dwordx4 v[68:69], v[50:53], off offset:528
	s_cbranch_vccnz .LBB0_1277
	v_ashrrev_i32_e32 v55, 31, v54
	v_lshlrev_b64 v[52:53], 12, v[54:55]
	v_lshl_add_u64 v[50:51], s[6:7], 0, v[52:53]
	s_mov_b64 s[44:45], 0

.LBB0_1279:
	v_lshl_add_u64 v[50:51], v[50:51], 0, v[166:167]
	global_load_dwordx4 v[234:237], v[50:51], off
	global_load_dwordx4 v[238:241], v[50:51], off offset:16
	global_load_dwordx4 v[242:245], v[50:51], off offset:512
	global_load_dwordx4 v[246:249], v[50:51], off offset:528
	v_lshl_add_u64 v[52:53], s[88:89], 0, v[52:53]
	v_lshl_add_u64 v[52:53], v[52:53], 0, v[166:167]
	s_and_b64 vcc, exec, s[4:5]
	s_mov_b64 s[44:45], -1
	s_waitcnt vmcnt(3)
	v_pk_mul_f32 v[236:237], v[236:237], s[22:23] op_sel_hi:[1,0]
	v_pk_mul_f32 v[234:235], v[234:235], s[22:23] op_sel_hi:[1,0]
	v_pk_fma_f32 v[48:49], v[48:49], v[124:125], v[236:237]
	v_pk_fma_f32 v[46:47], v[46:47], v[122:123], v[234:235]
	global_store_dwordx4 v[52:53], v[46:49], off
	s_nop 0
	s_waitcnt vmcnt(3)
	v_pk_mul_f32 v[240:241], v[240:241], s[22:23] op_sel_hi:[1,0]
	v_pk_mul_f32 v[238:239], v[238:239], s[22:23] op_sel_hi:[1,0]
	v_pk_fma_f32 v[44:45], v[44:45], v[116:117], v[240:241]
	v_pk_fma_f32 v[42:43], v[42:43], v[114:115], v[238:239]
	global_store_dwordx4 v[52:53], v[42:45], off offset:16
	s_nop 0
	s_waitcnt vmcnt(3)
	v_pk_mul_f32 v[244:245], v[244:245], s[22:23] op_sel_hi:[1,0]
	v_pk_mul_f32 v[242:243], v[242:243], s[22:23] op_sel_hi:[1,0]
	v_pk_fma_f32 v[40:41], v[40:41], v[112:113], v[244:245]
	v_pk_fma_f32 v[38:39], v[38:39], v[110:111], v[242:243]
	global_store_dwordx4 v[52:53], v[38:41], off offset:512
	s_nop 0
	s_waitcnt vmcnt(3)
	v_pk_mul_f32 v[248:249], v[248:249], s[22:23] op_sel_hi:[1,0]
	v_pk_mul_f32 v[246:247], v[246:247], s[22:23] op_sel_hi:[1,0]
	v_add_u32_e32 v38, 0xa0, v164
	v_pk_fma_f32 v[34:35], v[34:35], v[106:107], v[246:247]
	v_pk_fma_f32 v[36:37], v[36:37], v[108:109], v[248:249]
	global_store_dwordx4 v[52:53], v[34:37], off offset:528
	s_cbranch_vccnz .LBB0_1281
	v_ashrrev_i32_e32 v39, 31, v38
	v_lshlrev_b64 v[36:37], 12, v[38:39]
	v_lshl_add_u64 v[34:35], s[6:7], 0, v[36:37]
	s_mov_b64 s[44:45], 0

.LBB0_1283:
	v_lshl_add_u64 v[34:35], v[34:35], 0, v[166:167]
	global_load_dwordx4 v[234:237], v[34:35], off
	global_load_dwordx4 v[238:241], v[34:35], off offset:16
	global_load_dwordx4 v[242:245], v[34:35], off offset:512
	global_load_dwordx4 v[246:249], v[34:35], off offset:528
	v_lshl_add_u64 v[36:37], s[88:89], 0, v[36:37]
	v_lshl_add_u64 v[36:37], v[36:37], 0, v[166:167]
	s_and_b64 vcc, exec, s[4:5]
	s_mov_b64 s[4:5], -1
	s_waitcnt vmcnt(3)
	v_pk_mul_f32 v[236:237], v[236:237], s[22:23] op_sel_hi:[1,0]
	v_pk_mul_f32 v[234:235], v[234:235], s[22:23] op_sel_hi:[1,0]
	v_pk_fma_f32 v[32:33], v[32:33], v[124:125], v[236:237]
	v_pk_fma_f32 v[30:31], v[30:31], v[122:123], v[234:235]
	global_store_dwordx4 v[36:37], v[30:33], off
	s_nop 0
	s_waitcnt vmcnt(3)
	v_pk_mul_f32 v[240:241], v[240:241], s[22:23] op_sel_hi:[1,0]
	v_pk_mul_f32 v[238:239], v[238:239], s[22:23] op_sel_hi:[1,0]
	v_pk_fma_f32 v[28:29], v[28:29], v[116:117], v[240:241]
	v_pk_fma_f32 v[26:27], v[26:27], v[114:115], v[238:239]
	global_store_dwordx4 v[36:37], v[26:29], off offset:16
	s_nop 0
	s_waitcnt vmcnt(3)
	v_pk_mul_f32 v[244:245], v[244:245], s[22:23] op_sel_hi:[1,0]
	v_pk_mul_f32 v[242:243], v[242:243], s[22:23] op_sel_hi:[1,0]
	v_pk_fma_f32 v[24:25], v[24:25], v[112:113], v[244:245]
	v_pk_fma_f32 v[22:23], v[22:23], v[110:111], v[242:243]
	global_store_dwordx4 v[36:37], v[22:25], off offset:512
	s_nop 0
	s_waitcnt vmcnt(3)
	v_pk_mul_f32 v[248:249], v[248:249], s[22:23] op_sel_hi:[1,0]
	v_pk_mul_f32 v[246:247], v[246:247], s[22:23] op_sel_hi:[1,0]
	v_add_u32_e32 v22, 0xb0, v164
	v_pk_fma_f32 v[18:19], v[18:19], v[106:107], v[246:247]
	v_pk_fma_f32 v[20:21], v[20:21], v[108:109], v[248:249]
	global_store_dwordx4 v[36:37], v[18:21], off offset:528
	s_cbranch_vccnz .LBB0_1285
	v_ashrrev_i32_e32 v23, 31, v22
	v_lshlrev_b64 v[20:21], 12, v[22:23]
	v_lshl_add_u64 v[18:19], s[6:7], 0, v[20:21]
	s_mov_b64 s[4:5], 0

.LBB0_1287:
	v_lshl_add_u64 v[18:19], v[18:19], 0, v[166:167]
	global_load_dwordx4 v[234:237], v[18:19], off
	global_load_dwordx4 v[238:241], v[18:19], off offset:16
	global_load_dwordx4 v[242:245], v[18:19], off offset:512
	global_load_dwordx4 v[246:249], v[18:19], off offset:528
	v_lshl_add_u64 v[20:21], s[88:89], 0, v[20:21]
	v_lshl_add_u64 v[20:21], v[20:21], 0, v[166:167]
	s_and_b64 vcc, exec, s[2:3]
	s_mov_b64 s[2:3], -1
	s_waitcnt vmcnt(3)
	v_pk_mul_f32 v[236:237], v[236:237], s[22:23] op_sel_hi:[1,0]
	v_pk_mul_f32 v[234:235], v[234:235], s[22:23] op_sel_hi:[1,0]
	v_pk_fma_f32 v[16:17], v[16:17], v[124:125], v[236:237]
	v_pk_fma_f32 v[14:15], v[14:15], v[122:123], v[234:235]
	global_store_dwordx4 v[20:21], v[14:17], off
	s_nop 0
	s_waitcnt vmcnt(3)
	v_pk_mul_f32 v[240:241], v[240:241], s[22:23] op_sel_hi:[1,0]
	v_pk_mul_f32 v[238:239], v[238:239], s[22:23] op_sel_hi:[1,0]
	v_pk_fma_f32 v[12:13], v[12:13], v[116:117], v[240:241]
	v_pk_fma_f32 v[10:11], v[10:11], v[114:115], v[238:239]
	global_store_dwordx4 v[20:21], v[10:13], off offset:16
	s_nop 0
	s_waitcnt vmcnt(3)
	v_pk_mul_f32 v[244:245], v[244:245], s[22:23] op_sel_hi:[1,0]
	v_pk_mul_f32 v[242:243], v[242:243], s[22:23] op_sel_hi:[1,0]
	v_pk_fma_f32 v[8:9], v[8:9], v[112:113], v[244:245]
	v_pk_fma_f32 v[6:7], v[6:7], v[110:111], v[242:243]
	global_store_dwordx4 v[20:21], v[6:9], off offset:512
	s_nop 0
	s_waitcnt vmcnt(3)
	v_pk_mul_f32 v[248:249], v[248:249], s[22:23] op_sel_hi:[1,0]
	v_pk_mul_f32 v[246:247], v[246:247], s[22:23] op_sel_hi:[1,0]
	v_pk_fma_f32 v[4:5], v[4:5], v[108:109], v[248:249]
	v_pk_fma_f32 v[2:3], v[2:3], v[106:107], v[246:247]
	global_store_dwordx4 v[20:21], v[2:5], off offset:528
	s_cbranch_vccnz .LBB0_1240
	s_andn2_b64 vcc, exec, s[12:13]
	s_cbranch_vccnz .LBB0_1239
	s_barrier
	s_branch .LBB0_1239

.LBB0_1746:
	v_lshlrev_b64 v[166:167], 2, v[166:167]
	v_lshl_add_u64 v[168:169], v[168:169], 0, v[166:167]
	global_load_dwordx4 v[234:237], v[168:169], off
	global_load_dwordx4 v[238:241], v[168:169], off offset:16
	global_load_dwordx4 v[242:245], v[168:169], off offset:512
	global_load_dwordx4 v[246:249], v[168:169], off offset:528
	v_lshl_add_u64 v[170:171], s[88:89], 0, v[170:171]
	v_lshl_add_u64 v[170:171], v[170:171], 0, v[166:167]
	s_andn2_b64 vcc, exec, s[46:47]
	s_waitcnt vmcnt(3)
	v_pk_mul_f32 v[236:237], v[236:237], s[20:21] op_sel_hi:[1,0]
	v_pk_mul_f32 v[234:235], v[234:235], s[20:21] op_sel_hi:[1,0]
	v_pk_fma_f32 v[144:145], v[144:145], v[124:125], v[236:237]
	v_pk_fma_f32 v[142:143], v[142:143], v[122:123], v[234:235]
	global_store_dwordx4 v[170:171], v[142:145], off
	s_nop 0
	s_waitcnt vmcnt(3)
	v_pk_mul_f32 v[240:241], v[240:241], s[20:21] op_sel_hi:[1,0]
	v_pk_mul_f32 v[238:239], v[238:239], s[20:21] op_sel_hi:[1,0]
	v_pk_fma_f32 v[140:141], v[140:141], v[116:117], v[240:241]
	v_pk_fma_f32 v[138:139], v[138:139], v[114:115], v[238:239]
	global_store_dwordx4 v[170:171], v[138:141], off offset:16
	s_nop 0
	s_waitcnt vmcnt(3)
	v_pk_mul_f32 v[244:245], v[244:245], s[20:21] op_sel_hi:[1,0]
	v_pk_mul_f32 v[242:243], v[242:243], s[20:21] op_sel_hi:[1,0]
	v_pk_fma_f32 v[136:137], v[136:137], v[112:113], v[244:245]
	v_pk_fma_f32 v[134:135], v[134:135], v[110:111], v[242:243]
	global_store_dwordx4 v[170:171], v[134:137], off offset:512
	s_nop 0
	s_waitcnt vmcnt(3)
	v_pk_mul_f32 v[248:249], v[248:249], s[20:21] op_sel_hi:[1,0]
	v_cndmask_b32_e64 v135, 0, 1, s[46:47]
	v_pk_mul_f32 v[246:247], v[246:247], s[20:21] op_sel_hi:[1,0]
	v_or_b32_e32 v134, 16, v164
	v_cmp_ne_u32_e64 s[4:5], 1, v135
	v_pk_fma_f32 v[130:131], v[130:131], v[102:103], v[246:247]
	v_pk_fma_f32 v[132:133], v[132:133], v[104:105], v[248:249]
	s_mov_b64 s[46:47], -1
	global_store_dwordx4 v[170:171], v[130:133], off offset:528
	s_cbranch_vccnz .LBB0_1748
	v_ashrrev_i32_e32 v135, 31, v134
	v_lshlrev_b64 v[132:133], 12, v[134:135]
	v_lshl_add_u64 v[130:131], s[6:7], 0, v[132:133]
	s_mov_b64 s[46:47], 0

.LBB0_1750:
	v_lshl_add_u64 v[130:131], v[130:131], 0, v[166:167]
	global_load_dwordx4 v[234:237], v[130:131], off
	global_load_dwordx4 v[238:241], v[130:131], off offset:16
	global_load_dwordx4 v[242:245], v[130:131], off offset:512
	global_load_dwordx4 v[246:249], v[130:131], off offset:528
	v_lshl_add_u64 v[132:133], s[88:89], 0, v[132:133]
	v_lshl_add_u64 v[132:133], v[132:133], 0, v[166:167]
	s_and_b64 vcc, exec, s[4:5]
	s_mov_b64 s[46:47], -1
	s_waitcnt vmcnt(3)
	v_pk_mul_f32 v[236:237], v[236:237], s[20:21] op_sel_hi:[1,0]
	v_pk_mul_f32 v[234:235], v[234:235], s[20:21] op_sel_hi:[1,0]
	v_pk_fma_f32 v[128:129], v[128:129], v[124:125], v[236:237]
	v_pk_fma_f32 v[126:127], v[126:127], v[122:123], v[234:235]
	global_store_dwordx4 v[132:133], v[126:129], off
	s_nop 0
	s_waitcnt vmcnt(3)
	v_pk_mul_f32 v[240:241], v[240:241], s[20:21] op_sel_hi:[1,0]
	v_pk_mul_f32 v[238:239], v[238:239], s[20:21] op_sel_hi:[1,0]
	v_pk_fma_f32 v[120:121], v[120:121], v[116:117], v[240:241]
	v_pk_fma_f32 v[118:119], v[118:119], v[114:115], v[238:239]
	global_store_dwordx4 v[132:133], v[118:121], off offset:16
	s_nop 0
	s_waitcnt vmcnt(3)
	v_pk_mul_f32 v[244:245], v[244:245], s[20:21] op_sel_hi:[1,0]
	v_pk_mul_f32 v[242:243], v[242:243], s[20:21] op_sel_hi:[1,0]
	v_pk_fma_f32 v[108:109], v[108:109], v[112:113], v[244:245]
	v_pk_fma_f32 v[106:107], v[106:107], v[110:111], v[242:243]
	global_store_dwordx4 v[132:133], v[106:109], off offset:512
	s_nop 0
	s_waitcnt vmcnt(3)
	v_pk_mul_f32 v[246:247], v[246:247], s[20:21] op_sel_hi:[1,0]
	v_pk_mul_f32 v[108:109], v[248:249], s[20:21] op_sel_hi:[1,0]
	v_or_b32_e32 v106, 32, v164
	v_pk_fma_f32 v[98:99], v[98:99], v[102:103], v[246:247]
	v_pk_fma_f32 v[100:101], v[100:101], v[104:105], v[108:109]
	global_store_dwordx4 v[132:133], v[98:101], off offset:528
	s_cbranch_vccnz .LBB0_1752
	v_ashrrev_i32_e32 v107, 31, v106
	v_lshlrev_b64 v[100:101], 12, v[106:107]
	v_lshl_add_u64 v[98:99], s[6:7], 0, v[100:101]
	s_mov_b64 s[46:47], 0

.LBB0_1754:
	v_lshl_add_u64 v[98:99], v[98:99], 0, v[166:167]
	global_load_dwordx4 v[234:237], v[98:99], off
	global_load_dwordx4 v[238:241], v[98:99], off offset:16
	global_load_dwordx4 v[242:245], v[98:99], off offset:512
	global_load_dwordx4 v[246:249], v[98:99], off offset:528
	v_lshl_add_u64 v[100:101], s[88:89], 0, v[100:101]
	v_lshl_add_u64 v[100:101], v[100:101], 0, v[166:167]
	s_and_b64 vcc, exec, s[4:5]
	s_mov_b64 s[46:47], -1
	s_waitcnt vmcnt(3)
	v_pk_mul_f32 v[236:237], v[236:237], s[20:21] op_sel_hi:[1,0]
	v_pk_mul_f32 v[234:235], v[234:235], s[20:21] op_sel_hi:[1,0]
	v_pk_fma_f32 v[96:97], v[96:97], v[124:125], v[236:237]
	v_pk_fma_f32 v[94:95], v[94:95], v[122:123], v[234:235]
	global_store_dwordx4 v[100:101], v[94:97], off
	s_nop 0
	s_waitcnt vmcnt(3)
	v_pk_mul_f32 v[240:241], v[240:241], s[20:21] op_sel_hi:[1,0]
	v_pk_mul_f32 v[238:239], v[238:239], s[20:21] op_sel_hi:[1,0]
	v_pk_fma_f32 v[92:93], v[92:93], v[116:117], v[240:241]
	v_pk_fma_f32 v[90:91], v[90:91], v[114:115], v[238:239]
	global_store_dwordx4 v[100:101], v[90:93], off offset:16
	s_nop 0
	s_waitcnt vmcnt(3)
	v_pk_mul_f32 v[244:245], v[244:245], s[20:21] op_sel_hi:[1,0]
	v_pk_mul_f32 v[242:243], v[242:243], s[20:21] op_sel_hi:[1,0]
	v_pk_fma_f32 v[88:89], v[88:89], v[112:113], v[244:245]
	v_pk_fma_f32 v[86:87], v[86:87], v[110:111], v[242:243]
	global_store_dwordx4 v[100:101], v[86:89], off offset:512
	s_nop 0
	s_waitcnt vmcnt(3)
	v_pk_mul_f32 v[248:249], v[248:249], s[20:21] op_sel_hi:[1,0]
	v_pk_mul_f32 v[246:247], v[246:247], s[20:21] op_sel_hi:[1,0]
	v_or_b32_e32 v86, 48, v164
	v_pk_fma_f32 v[82:83], v[82:83], v[102:103], v[246:247]
	v_pk_fma_f32 v[84:85], v[84:85], v[104:105], v[248:249]
	global_store_dwordx4 v[100:101], v[82:85], off offset:528
	s_cbranch_vccnz .LBB0_1756
	v_ashrrev_i32_e32 v87, 31, v86
	v_lshlrev_b64 v[84:85], 12, v[86:87]
	v_lshl_add_u64 v[82:83], s[6:7], 0, v[84:85]
	s_mov_b64 s[46:47], 0

.LBB0_1758:
	v_lshl_add_u64 v[82:83], v[82:83], 0, v[166:167]
	global_load_dwordx4 v[234:237], v[82:83], off
	global_load_dwordx4 v[238:241], v[82:83], off offset:16
	global_load_dwordx4 v[242:245], v[82:83], off offset:512
	global_load_dwordx4 v[246:249], v[82:83], off offset:528
	v_lshl_add_u64 v[84:85], s[88:89], 0, v[84:85]
	v_lshl_add_u64 v[84:85], v[84:85], 0, v[166:167]
	s_and_b64 vcc, exec, s[4:5]
	s_mov_b64 s[46:47], -1
	s_waitcnt vmcnt(3)
	v_pk_mul_f32 v[236:237], v[236:237], s[20:21] op_sel_hi:[1,0]
	v_pk_mul_f32 v[234:235], v[234:235], s[20:21] op_sel_hi:[1,0]
	v_pk_fma_f32 v[80:81], v[80:81], v[124:125], v[236:237]
	v_pk_fma_f32 v[78:79], v[78:79], v[122:123], v[234:235]
	global_store_dwordx4 v[84:85], v[78:81], off
	s_nop 0
	s_waitcnt vmcnt(3)
	v_pk_mul_f32 v[240:241], v[240:241], s[20:21] op_sel_hi:[1,0]
	v_pk_mul_f32 v[238:239], v[238:239], s[20:21] op_sel_hi:[1,0]
	v_pk_fma_f32 v[76:77], v[76:77], v[116:117], v[240:241]
	v_pk_fma_f32 v[74:75], v[74:75], v[114:115], v[238:239]
	global_store_dwordx4 v[84:85], v[74:77], off offset:16
	s_nop 0
	s_waitcnt vmcnt(3)
	v_pk_mul_f32 v[244:245], v[244:245], s[20:21] op_sel_hi:[1,0]
	v_pk_mul_f32 v[242:243], v[242:243], s[20:21] op_sel_hi:[1,0]
	v_pk_fma_f32 v[72:73], v[72:73], v[112:113], v[244:245]
	v_pk_fma_f32 v[70:71], v[70:71], v[110:111], v[242:243]
	global_store_dwordx4 v[84:85], v[70:73], off offset:512
	s_nop 0
	s_waitcnt vmcnt(3)
	v_pk_mul_f32 v[248:249], v[248:249], s[20:21] op_sel_hi:[1,0]
	v_pk_mul_f32 v[246:247], v[246:247], s[20:21] op_sel_hi:[1,0]
	v_add_u32_e32 v70, 0x80, v164
	v_pk_fma_f32 v[66:67], v[66:67], v[102:103], v[246:247]
	v_pk_fma_f32 v[68:69], v[68:69], v[104:105], v[248:249]
	global_store_dwordx4 v[84:85], v[66:69], off offset:528
	s_cbranch_vccnz .LBB0_1760
	v_ashrrev_i32_e32 v71, 31, v70
	v_lshlrev_b64 v[68:69], 12, v[70:71]
	v_lshl_add_u64 v[66:67], s[6:7], 0, v[68:69]
	s_mov_b64 s[46:47], 0

.LBB0_1762:
	v_lshl_add_u64 v[66:67], v[66:67], 0, v[166:167]
	global_load_dwordx4 v[234:237], v[66:67], off
	global_load_dwordx4 v[238:241], v[66:67], off offset:16
	global_load_dwordx4 v[242:245], v[66:67], off offset:512
	global_load_dwordx4 v[246:249], v[66:67], off offset:528
	v_lshl_add_u64 v[68:69], s[88:89], 0, v[68:69]
	v_lshl_add_u64 v[68:69], v[68:69], 0, v[166:167]
	s_and_b64 vcc, exec, s[4:5]
	s_mov_b64 s[46:47], -1
	s_waitcnt vmcnt(3)
	v_pk_mul_f32 v[236:237], v[236:237], s[20:21] op_sel_hi:[1,0]
	v_pk_mul_f32 v[234:235], v[234:235], s[20:21] op_sel_hi:[1,0]
	v_pk_fma_f32 v[64:65], v[64:65], v[124:125], v[236:237]
	v_pk_fma_f32 v[62:63], v[62:63], v[122:123], v[234:235]
	global_store_dwordx4 v[68:69], v[62:65], off
	s_nop 0
	s_waitcnt vmcnt(3)
	v_pk_mul_f32 v[240:241], v[240:241], s[20:21] op_sel_hi:[1,0]
	v_pk_mul_f32 v[238:239], v[238:239], s[20:21] op_sel_hi:[1,0]
	v_pk_fma_f32 v[60:61], v[60:61], v[116:117], v[240:241]
	v_pk_fma_f32 v[58:59], v[58:59], v[114:115], v[238:239]
	global_store_dwordx4 v[68:69], v[58:61], off offset:16
	s_nop 0
	s_waitcnt vmcnt(3)
	v_pk_mul_f32 v[244:245], v[244:245], s[20:21] op_sel_hi:[1,0]
	v_pk_mul_f32 v[242:243], v[242:243], s[20:21] op_sel_hi:[1,0]
	v_pk_fma_f32 v[56:57], v[56:57], v[112:113], v[244:245]
	v_pk_fma_f32 v[54:55], v[54:55], v[110:111], v[242:243]
	global_store_dwordx4 v[68:69], v[54:57], off offset:512
	s_nop 0
	s_waitcnt vmcnt(3)
	v_pk_mul_f32 v[248:249], v[248:249], s[20:21] op_sel_hi:[1,0]
	v_pk_mul_f32 v[246:247], v[246:247], s[20:21] op_sel_hi:[1,0]
	v_add_u32_e32 v54, 0x90, v164
	v_pk_fma_f32 v[50:51], v[50:51], v[102:103], v[246:247]
	v_pk_fma_f32 v[52:53], v[52:53], v[104:105], v[248:249]
	global_store_dwordx4 v[68:69], v[50:53], off offset:528
	s_cbranch_vccnz .LBB0_1764
	v_ashrrev_i32_e32 v55, 31, v54
	v_lshlrev_b64 v[52:53], 12, v[54:55]
	v_lshl_add_u64 v[50:51], s[6:7], 0, v[52:53]
	s_mov_b64 s[46:47], 0

.LBB0_1766:
	v_lshl_add_u64 v[50:51], v[50:51], 0, v[166:167]
	global_load_dwordx4 v[234:237], v[50:51], off
	global_load_dwordx4 v[238:241], v[50:51], off offset:16
	global_load_dwordx4 v[242:245], v[50:51], off offset:512
	global_load_dwordx4 v[246:249], v[50:51], off offset:528
	v_lshl_add_u64 v[52:53], s[88:89], 0, v[52:53]
	v_lshl_add_u64 v[52:53], v[52:53], 0, v[166:167]
	s_and_b64 vcc, exec, s[4:5]
	s_mov_b64 s[46:47], -1
	s_waitcnt vmcnt(3)
	v_pk_mul_f32 v[236:237], v[236:237], s[20:21] op_sel_hi:[1,0]
	v_pk_mul_f32 v[234:235], v[234:235], s[20:21] op_sel_hi:[1,0]
	v_pk_fma_f32 v[48:49], v[48:49], v[124:125], v[236:237]
	v_pk_fma_f32 v[46:47], v[46:47], v[122:123], v[234:235]
	global_store_dwordx4 v[52:53], v[46:49], off
	s_nop 0
	s_waitcnt vmcnt(3)
	v_pk_mul_f32 v[240:241], v[240:241], s[20:21] op_sel_hi:[1,0]
	v_pk_mul_f32 v[238:239], v[238:239], s[20:21] op_sel_hi:[1,0]
	v_pk_fma_f32 v[44:45], v[44:45], v[116:117], v[240:241]
	v_pk_fma_f32 v[42:43], v[42:43], v[114:115], v[238:239]
	global_store_dwordx4 v[52:53], v[42:45], off offset:16
	s_nop 0
	s_waitcnt vmcnt(3)
	v_pk_mul_f32 v[244:245], v[244:245], s[20:21] op_sel_hi:[1,0]
	v_pk_mul_f32 v[242:243], v[242:243], s[20:21] op_sel_hi:[1,0]
	v_pk_fma_f32 v[40:41], v[40:41], v[112:113], v[244:245]
	v_pk_fma_f32 v[38:39], v[38:39], v[110:111], v[242:243]
	global_store_dwordx4 v[52:53], v[38:41], off offset:512
	s_nop 0
	s_waitcnt vmcnt(3)
	v_pk_mul_f32 v[248:249], v[248:249], s[20:21] op_sel_hi:[1,0]
	v_pk_mul_f32 v[246:247], v[246:247], s[20:21] op_sel_hi:[1,0]
	v_add_u32_e32 v38, 0xa0, v164
	v_pk_fma_f32 v[34:35], v[34:35], v[102:103], v[246:247]
	v_pk_fma_f32 v[36:37], v[36:37], v[104:105], v[248:249]
	global_store_dwordx4 v[52:53], v[34:37], off offset:528
	s_cbranch_vccnz .LBB0_1768
	v_ashrrev_i32_e32 v39, 31, v38
	v_lshlrev_b64 v[36:37], 12, v[38:39]
	v_lshl_add_u64 v[34:35], s[6:7], 0, v[36:37]
	s_mov_b64 s[46:47], 0

.LBB0_1770:
	v_lshl_add_u64 v[34:35], v[34:35], 0, v[166:167]
	global_load_dwordx4 v[234:237], v[34:35], off
	global_load_dwordx4 v[238:241], v[34:35], off offset:16
	global_load_dwordx4 v[242:245], v[34:35], off offset:512
	global_load_dwordx4 v[246:249], v[34:35], off offset:528
	v_lshl_add_u64 v[36:37], s[88:89], 0, v[36:37]
	v_lshl_add_u64 v[36:37], v[36:37], 0, v[166:167]
	s_and_b64 vcc, exec, s[4:5]
	s_mov_b64 s[4:5], -1
	s_waitcnt vmcnt(3)
	v_pk_mul_f32 v[236:237], v[236:237], s[20:21] op_sel_hi:[1,0]
	v_pk_mul_f32 v[234:235], v[234:235], s[20:21] op_sel_hi:[1,0]
	v_pk_fma_f32 v[32:33], v[32:33], v[124:125], v[236:237]
	v_pk_fma_f32 v[30:31], v[30:31], v[122:123], v[234:235]
	global_store_dwordx4 v[36:37], v[30:33], off
	s_nop 0
	s_waitcnt vmcnt(3)
	v_pk_mul_f32 v[240:241], v[240:241], s[20:21] op_sel_hi:[1,0]
	v_pk_mul_f32 v[238:239], v[238:239], s[20:21] op_sel_hi:[1,0]
	v_pk_fma_f32 v[28:29], v[28:29], v[116:117], v[240:241]
	v_pk_fma_f32 v[26:27], v[26:27], v[114:115], v[238:239]
	global_store_dwordx4 v[36:37], v[26:29], off offset:16
	s_nop 0
	s_waitcnt vmcnt(3)
	v_pk_mul_f32 v[244:245], v[244:245], s[20:21] op_sel_hi:[1,0]
	v_pk_mul_f32 v[242:243], v[242:243], s[20:21] op_sel_hi:[1,0]
	v_pk_fma_f32 v[24:25], v[24:25], v[112:113], v[244:245]
	v_pk_fma_f32 v[22:23], v[22:23], v[110:111], v[242:243]
	global_store_dwordx4 v[36:37], v[22:25], off offset:512
	s_nop 0
	s_waitcnt vmcnt(3)
	v_pk_mul_f32 v[248:249], v[248:249], s[20:21] op_sel_hi:[1,0]
	v_pk_mul_f32 v[246:247], v[246:247], s[20:21] op_sel_hi:[1,0]
	v_add_u32_e32 v22, 0xb0, v164
	v_pk_fma_f32 v[18:19], v[18:19], v[102:103], v[246:247]
	v_pk_fma_f32 v[20:21], v[20:21], v[104:105], v[248:249]
	global_store_dwordx4 v[36:37], v[18:21], off offset:528
	s_cbranch_vccnz .LBB0_1772
	v_ashrrev_i32_e32 v23, 31, v22
	v_lshlrev_b64 v[20:21], 12, v[22:23]
	v_lshl_add_u64 v[18:19], s[6:7], 0, v[20:21]
	s_mov_b64 s[4:5], 0

.LBB0_1774:
	v_lshl_add_u64 v[18:19], v[18:19], 0, v[166:167]
	global_load_dwordx4 v[234:237], v[18:19], off
	global_load_dwordx4 v[238:241], v[18:19], off offset:16
	global_load_dwordx4 v[242:245], v[18:19], off offset:512
	global_load_dwordx4 v[246:249], v[18:19], off offset:528
	v_lshl_add_u64 v[20:21], s[88:89], 0, v[20:21]
	v_lshl_add_u64 v[20:21], v[20:21], 0, v[166:167]
	s_andn2_b64 vcc, exec, s[2:3]
	s_mov_b64 s[2:3], -1
	s_waitcnt vmcnt(3)
	v_pk_mul_f32 v[236:237], v[236:237], s[20:21] op_sel_hi:[1,0]
	v_pk_mul_f32 v[234:235], v[234:235], s[20:21] op_sel_hi:[1,0]
	v_pk_fma_f32 v[16:17], v[16:17], v[124:125], v[236:237]
	v_pk_fma_f32 v[14:15], v[14:15], v[122:123], v[234:235]
	global_store_dwordx4 v[20:21], v[14:17], off
	s_nop 0
	s_waitcnt vmcnt(3)
	v_pk_mul_f32 v[240:241], v[240:241], s[20:21] op_sel_hi:[1,0]
	v_pk_mul_f32 v[238:239], v[238:239], s[20:21] op_sel_hi:[1,0]
	v_pk_fma_f32 v[12:13], v[12:13], v[116:117], v[240:241]
	v_pk_fma_f32 v[10:11], v[10:11], v[114:115], v[238:239]
	global_store_dwordx4 v[20:21], v[10:13], off offset:16
	s_nop 0
	s_waitcnt vmcnt(3)
	v_pk_mul_f32 v[244:245], v[244:245], s[20:21] op_sel_hi:[1,0]
	v_pk_mul_f32 v[242:243], v[242:243], s[20:21] op_sel_hi:[1,0]
	v_pk_fma_f32 v[8:9], v[8:9], v[112:113], v[244:245]
	v_pk_fma_f32 v[6:7], v[6:7], v[110:111], v[242:243]
	global_store_dwordx4 v[20:21], v[6:9], off offset:512
	s_nop 0
	s_waitcnt vmcnt(3)
	v_pk_mul_f32 v[248:249], v[248:249], s[20:21] op_sel_hi:[1,0]
	v_pk_mul_f32 v[246:247], v[246:247], s[20:21] op_sel_hi:[1,0]
	v_pk_fma_f32 v[4:5], v[4:5], v[104:105], v[248:249]
	v_pk_fma_f32 v[2:3], v[2:3], v[102:103], v[246:247]
	global_store_dwordx4 v[20:21], v[2:5], off offset:528
	s_cbranch_vccnz .LBB0_1731
	s_andn2_b64 vcc, exec, s[10:11]
	s_cbranch_vccnz .LBB0_1730
	s_barrier
	s_branch .LBB0_1730

.LBB0_2029:
	v_lshlrev_b64 v[166:167], 2, v[166:167]
	v_lshl_add_u64 v[168:169], v[168:169], 0, v[166:167]
	global_load_dwordx4 v[234:237], v[168:169], off
	global_load_dwordx4 v[238:241], v[168:169], off offset:16
	global_load_dwordx4 v[242:245], v[168:169], off offset:512
	global_load_dwordx4 v[246:249], v[168:169], off offset:528
	v_lshl_add_u64 v[170:171], s[88:89], 0, v[170:171]
	v_lshl_add_u64 v[170:171], v[170:171], 0, v[166:167]
	s_andn2_b64 vcc, exec, s[42:43]
	s_waitcnt vmcnt(3)
	v_pk_mul_f32 v[236:237], v[236:237], s[20:21] op_sel_hi:[1,0]
	v_pk_mul_f32 v[234:235], v[234:235], s[20:21] op_sel_hi:[1,0]
	v_pk_fma_f32 v[144:145], v[144:145], v[124:125], v[236:237]
	v_pk_fma_f32 v[142:143], v[142:143], v[122:123], v[234:235]
	global_store_dwordx4 v[170:171], v[142:145], off
	s_nop 0
	s_waitcnt vmcnt(3)
	v_pk_mul_f32 v[240:241], v[240:241], s[20:21] op_sel_hi:[1,0]
	v_pk_mul_f32 v[238:239], v[238:239], s[20:21] op_sel_hi:[1,0]
	v_pk_fma_f32 v[140:141], v[140:141], v[116:117], v[240:241]
	v_pk_fma_f32 v[138:139], v[138:139], v[114:115], v[238:239]
	global_store_dwordx4 v[170:171], v[138:141], off offset:16
	s_nop 0
	s_waitcnt vmcnt(3)
	v_pk_mul_f32 v[244:245], v[244:245], s[20:21] op_sel_hi:[1,0]
	v_pk_mul_f32 v[242:243], v[242:243], s[20:21] op_sel_hi:[1,0]
	v_pk_fma_f32 v[136:137], v[136:137], v[112:113], v[244:245]
	v_pk_fma_f32 v[134:135], v[134:135], v[110:111], v[242:243]
	global_store_dwordx4 v[170:171], v[134:137], off offset:512
	s_nop 0
	s_waitcnt vmcnt(3)
	v_pk_mul_f32 v[248:249], v[248:249], s[20:21] op_sel_hi:[1,0]
	v_cndmask_b32_e64 v135, 0, 1, s[42:43]
	v_pk_mul_f32 v[246:247], v[246:247], s[20:21] op_sel_hi:[1,0]
	v_or_b32_e32 v134, 16, v164
	v_cmp_ne_u32_e64 s[4:5], 1, v135
	v_pk_fma_f32 v[130:131], v[130:131], v[106:107], v[246:247]
	v_pk_fma_f32 v[132:133], v[132:133], v[108:109], v[248:249]
	s_mov_b64 s[42:43], -1
	global_store_dwordx4 v[170:171], v[130:133], off offset:528
	s_cbranch_vccnz .LBB0_2031
	v_ashrrev_i32_e32 v135, 31, v134
	v_lshlrev_b64 v[132:133], 12, v[134:135]
	v_lshl_add_u64 v[130:131], s[6:7], 0, v[132:133]
	s_mov_b64 s[42:43], 0

.LBB0_2033:
	v_lshl_add_u64 v[130:131], v[130:131], 0, v[166:167]
	global_load_dwordx4 v[234:237], v[130:131], off
	global_load_dwordx4 v[238:241], v[130:131], off offset:16
	global_load_dwordx4 v[242:245], v[130:131], off offset:512
	global_load_dwordx4 v[246:249], v[130:131], off offset:528
	v_lshl_add_u64 v[132:133], s[88:89], 0, v[132:133]
	v_lshl_add_u64 v[132:133], v[132:133], 0, v[166:167]
	s_and_b64 vcc, exec, s[4:5]
	s_mov_b64 s[42:43], -1
	s_waitcnt vmcnt(3)
	v_pk_mul_f32 v[236:237], v[236:237], s[20:21] op_sel_hi:[1,0]
	v_pk_mul_f32 v[234:235], v[234:235], s[20:21] op_sel_hi:[1,0]
	v_pk_fma_f32 v[128:129], v[128:129], v[124:125], v[236:237]
	v_pk_fma_f32 v[126:127], v[126:127], v[122:123], v[234:235]
	global_store_dwordx4 v[132:133], v[126:129], off
	s_nop 0
	s_waitcnt vmcnt(3)
	v_pk_mul_f32 v[240:241], v[240:241], s[20:21] op_sel_hi:[1,0]
	v_pk_mul_f32 v[238:239], v[238:239], s[20:21] op_sel_hi:[1,0]
	v_pk_fma_f32 v[120:121], v[120:121], v[116:117], v[240:241]
	v_pk_fma_f32 v[118:119], v[118:119], v[114:115], v[238:239]
	global_store_dwordx4 v[132:133], v[118:121], off offset:16
	s_nop 0
	s_waitcnt vmcnt(3)
	v_pk_mul_f32 v[244:245], v[244:245], s[20:21] op_sel_hi:[1,0]
	v_pk_mul_f32 v[242:243], v[242:243], s[20:21] op_sel_hi:[1,0]
	v_pk_fma_f32 v[104:105], v[104:105], v[112:113], v[244:245]
	v_pk_fma_f32 v[102:103], v[102:103], v[110:111], v[242:243]
	global_store_dwordx4 v[132:133], v[102:105], off offset:512
	s_nop 0
	s_waitcnt vmcnt(3)
	v_pk_mul_f32 v[246:247], v[246:247], s[20:21] op_sel_hi:[1,0]
	v_pk_mul_f32 v[104:105], v[248:249], s[20:21] op_sel_hi:[1,0]
	v_or_b32_e32 v102, 32, v164
	v_pk_fma_f32 v[98:99], v[98:99], v[106:107], v[246:247]
	v_pk_fma_f32 v[100:101], v[100:101], v[108:109], v[104:105]
	global_store_dwordx4 v[132:133], v[98:101], off offset:528
	s_cbranch_vccnz .LBB0_2035
	v_ashrrev_i32_e32 v103, 31, v102
	v_lshlrev_b64 v[100:101], 12, v[102:103]
	v_lshl_add_u64 v[98:99], s[6:7], 0, v[100:101]
	s_mov_b64 s[42:43], 0

.LBB0_2037:
	v_lshl_add_u64 v[98:99], v[98:99], 0, v[166:167]
	global_load_dwordx4 v[234:237], v[98:99], off
	global_load_dwordx4 v[238:241], v[98:99], off offset:16
	global_load_dwordx4 v[242:245], v[98:99], off offset:512
	global_load_dwordx4 v[246:249], v[98:99], off offset:528
	v_lshl_add_u64 v[100:101], s[88:89], 0, v[100:101]
	v_lshl_add_u64 v[100:101], v[100:101], 0, v[166:167]
	s_and_b64 vcc, exec, s[4:5]
	s_mov_b64 s[42:43], -1
	s_waitcnt vmcnt(3)
	v_pk_mul_f32 v[236:237], v[236:237], s[20:21] op_sel_hi:[1,0]
	v_pk_mul_f32 v[234:235], v[234:235], s[20:21] op_sel_hi:[1,0]
	v_pk_fma_f32 v[96:97], v[96:97], v[124:125], v[236:237]
	v_pk_fma_f32 v[94:95], v[94:95], v[122:123], v[234:235]
	global_store_dwordx4 v[100:101], v[94:97], off
	s_nop 0
	s_waitcnt vmcnt(3)
	v_pk_mul_f32 v[240:241], v[240:241], s[20:21] op_sel_hi:[1,0]
	v_pk_mul_f32 v[238:239], v[238:239], s[20:21] op_sel_hi:[1,0]
	v_pk_fma_f32 v[92:93], v[92:93], v[116:117], v[240:241]
	v_pk_fma_f32 v[90:91], v[90:91], v[114:115], v[238:239]
	global_store_dwordx4 v[100:101], v[90:93], off offset:16
	s_nop 0
	s_waitcnt vmcnt(3)
	v_pk_mul_f32 v[244:245], v[244:245], s[20:21] op_sel_hi:[1,0]
	v_pk_mul_f32 v[242:243], v[242:243], s[20:21] op_sel_hi:[1,0]
	v_pk_fma_f32 v[88:89], v[88:89], v[112:113], v[244:245]
	v_pk_fma_f32 v[86:87], v[86:87], v[110:111], v[242:243]
	global_store_dwordx4 v[100:101], v[86:89], off offset:512
	s_nop 0
	s_waitcnt vmcnt(3)
	v_pk_mul_f32 v[248:249], v[248:249], s[20:21] op_sel_hi:[1,0]
	v_pk_mul_f32 v[246:247], v[246:247], s[20:21] op_sel_hi:[1,0]
	v_or_b32_e32 v86, 48, v164
	v_pk_fma_f32 v[82:83], v[82:83], v[106:107], v[246:247]
	v_pk_fma_f32 v[84:85], v[84:85], v[108:109], v[248:249]
	global_store_dwordx4 v[100:101], v[82:85], off offset:528
	s_cbranch_vccnz .LBB0_2039
	v_ashrrev_i32_e32 v87, 31, v86
	v_lshlrev_b64 v[84:85], 12, v[86:87]
	v_lshl_add_u64 v[82:83], s[6:7], 0, v[84:85]
	s_mov_b64 s[42:43], 0

.LBB0_2041:
	v_lshl_add_u64 v[82:83], v[82:83], 0, v[166:167]
	global_load_dwordx4 v[234:237], v[82:83], off
	global_load_dwordx4 v[238:241], v[82:83], off offset:16
	global_load_dwordx4 v[242:245], v[82:83], off offset:512
	global_load_dwordx4 v[246:249], v[82:83], off offset:528
	v_lshl_add_u64 v[84:85], s[88:89], 0, v[84:85]
	v_lshl_add_u64 v[84:85], v[84:85], 0, v[166:167]
	s_and_b64 vcc, exec, s[4:5]
	s_mov_b64 s[42:43], -1
	s_waitcnt vmcnt(3)
	v_pk_mul_f32 v[236:237], v[236:237], s[20:21] op_sel_hi:[1,0]
	v_pk_mul_f32 v[234:235], v[234:235], s[20:21] op_sel_hi:[1,0]
	v_pk_fma_f32 v[80:81], v[80:81], v[124:125], v[236:237]
	v_pk_fma_f32 v[78:79], v[78:79], v[122:123], v[234:235]
	global_store_dwordx4 v[84:85], v[78:81], off
	s_nop 0
	s_waitcnt vmcnt(3)
	v_pk_mul_f32 v[240:241], v[240:241], s[20:21] op_sel_hi:[1,0]
	v_pk_mul_f32 v[238:239], v[238:239], s[20:21] op_sel_hi:[1,0]
	v_pk_fma_f32 v[76:77], v[76:77], v[116:117], v[240:241]
	v_pk_fma_f32 v[74:75], v[74:75], v[114:115], v[238:239]
	global_store_dwordx4 v[84:85], v[74:77], off offset:16
	s_nop 0
	s_waitcnt vmcnt(3)
	v_pk_mul_f32 v[244:245], v[244:245], s[20:21] op_sel_hi:[1,0]
	v_pk_mul_f32 v[242:243], v[242:243], s[20:21] op_sel_hi:[1,0]
	v_pk_fma_f32 v[72:73], v[72:73], v[112:113], v[244:245]
	v_pk_fma_f32 v[70:71], v[70:71], v[110:111], v[242:243]
	global_store_dwordx4 v[84:85], v[70:73], off offset:512
	s_nop 0
	s_waitcnt vmcnt(3)
	v_pk_mul_f32 v[248:249], v[248:249], s[20:21] op_sel_hi:[1,0]
	v_pk_mul_f32 v[246:247], v[246:247], s[20:21] op_sel_hi:[1,0]
	v_add_u32_e32 v70, 0x80, v164
	v_pk_fma_f32 v[66:67], v[66:67], v[106:107], v[246:247]
	v_pk_fma_f32 v[68:69], v[68:69], v[108:109], v[248:249]
	global_store_dwordx4 v[84:85], v[66:69], off offset:528
	s_cbranch_vccnz .LBB0_2043
	v_ashrrev_i32_e32 v71, 31, v70
	v_lshlrev_b64 v[68:69], 12, v[70:71]
	v_lshl_add_u64 v[66:67], s[6:7], 0, v[68:69]
	s_mov_b64 s[42:43], 0

.LBB0_2045:
	v_lshl_add_u64 v[66:67], v[66:67], 0, v[166:167]
	global_load_dwordx4 v[234:237], v[66:67], off
	global_load_dwordx4 v[238:241], v[66:67], off offset:16
	global_load_dwordx4 v[242:245], v[66:67], off offset:512
	global_load_dwordx4 v[246:249], v[66:67], off offset:528
	v_lshl_add_u64 v[68:69], s[88:89], 0, v[68:69]
	v_lshl_add_u64 v[68:69], v[68:69], 0, v[166:167]
	s_and_b64 vcc, exec, s[4:5]
	s_mov_b64 s[42:43], -1
	s_waitcnt vmcnt(3)
	v_pk_mul_f32 v[236:237], v[236:237], s[20:21] op_sel_hi:[1,0]
	v_pk_mul_f32 v[234:235], v[234:235], s[20:21] op_sel_hi:[1,0]
	v_pk_fma_f32 v[64:65], v[64:65], v[124:125], v[236:237]
	v_pk_fma_f32 v[62:63], v[62:63], v[122:123], v[234:235]
	global_store_dwordx4 v[68:69], v[62:65], off
	s_nop 0
	s_waitcnt vmcnt(3)
	v_pk_mul_f32 v[240:241], v[240:241], s[20:21] op_sel_hi:[1,0]
	v_pk_mul_f32 v[238:239], v[238:239], s[20:21] op_sel_hi:[1,0]
	v_pk_fma_f32 v[60:61], v[60:61], v[116:117], v[240:241]
	v_pk_fma_f32 v[58:59], v[58:59], v[114:115], v[238:239]
	global_store_dwordx4 v[68:69], v[58:61], off offset:16
	s_nop 0
	s_waitcnt vmcnt(3)
	v_pk_mul_f32 v[244:245], v[244:245], s[20:21] op_sel_hi:[1,0]
	v_pk_mul_f32 v[242:243], v[242:243], s[20:21] op_sel_hi:[1,0]
	v_pk_fma_f32 v[56:57], v[56:57], v[112:113], v[244:245]
	v_pk_fma_f32 v[54:55], v[54:55], v[110:111], v[242:243]
	global_store_dwordx4 v[68:69], v[54:57], off offset:512
	s_nop 0
	s_waitcnt vmcnt(3)
	v_pk_mul_f32 v[248:249], v[248:249], s[20:21] op_sel_hi:[1,0]
	v_pk_mul_f32 v[246:247], v[246:247], s[20:21] op_sel_hi:[1,0]
	v_add_u32_e32 v54, 0x90, v164
	v_pk_fma_f32 v[50:51], v[50:51], v[106:107], v[246:247]
	v_pk_fma_f32 v[52:53], v[52:53], v[108:109], v[248:249]
	global_store_dwordx4 v[68:69], v[50:53], off offset:528
	s_cbranch_vccnz .LBB0_2047
	v_ashrrev_i32_e32 v55, 31, v54
	v_lshlrev_b64 v[52:53], 12, v[54:55]
	v_lshl_add_u64 v[50:51], s[6:7], 0, v[52:53]
	s_mov_b64 s[42:43], 0

.LBB0_2049:
	v_lshl_add_u64 v[50:51], v[50:51], 0, v[166:167]
	global_load_dwordx4 v[234:237], v[50:51], off
	global_load_dwordx4 v[238:241], v[50:51], off offset:16
	global_load_dwordx4 v[242:245], v[50:51], off offset:512
	global_load_dwordx4 v[246:249], v[50:51], off offset:528
	v_lshl_add_u64 v[52:53], s[88:89], 0, v[52:53]
	v_lshl_add_u64 v[52:53], v[52:53], 0, v[166:167]
	s_and_b64 vcc, exec, s[4:5]
	s_mov_b64 s[42:43], -1
	s_waitcnt vmcnt(3)
	v_pk_mul_f32 v[236:237], v[236:237], s[20:21] op_sel_hi:[1,0]
	v_pk_mul_f32 v[234:235], v[234:235], s[20:21] op_sel_hi:[1,0]
	v_pk_fma_f32 v[48:49], v[48:49], v[124:125], v[236:237]
	v_pk_fma_f32 v[46:47], v[46:47], v[122:123], v[234:235]
	global_store_dwordx4 v[52:53], v[46:49], off
	s_nop 0
	s_waitcnt vmcnt(3)
	v_pk_mul_f32 v[240:241], v[240:241], s[20:21] op_sel_hi:[1,0]
	v_pk_mul_f32 v[238:239], v[238:239], s[20:21] op_sel_hi:[1,0]
	v_pk_fma_f32 v[44:45], v[44:45], v[116:117], v[240:241]
	v_pk_fma_f32 v[42:43], v[42:43], v[114:115], v[238:239]
	global_store_dwordx4 v[52:53], v[42:45], off offset:16
	s_nop 0
	s_waitcnt vmcnt(3)
	v_pk_mul_f32 v[244:245], v[244:245], s[20:21] op_sel_hi:[1,0]
	v_pk_mul_f32 v[242:243], v[242:243], s[20:21] op_sel_hi:[1,0]
	v_pk_fma_f32 v[40:41], v[40:41], v[112:113], v[244:245]
	v_pk_fma_f32 v[38:39], v[38:39], v[110:111], v[242:243]
	global_store_dwordx4 v[52:53], v[38:41], off offset:512
	s_nop 0
	s_waitcnt vmcnt(3)
	v_pk_mul_f32 v[248:249], v[248:249], s[20:21] op_sel_hi:[1,0]
	v_pk_mul_f32 v[246:247], v[246:247], s[20:21] op_sel_hi:[1,0]
	v_add_u32_e32 v38, 0xa0, v164
	v_pk_fma_f32 v[34:35], v[34:35], v[106:107], v[246:247]
	v_pk_fma_f32 v[36:37], v[36:37], v[108:109], v[248:249]
	global_store_dwordx4 v[52:53], v[34:37], off offset:528
	s_cbranch_vccnz .LBB0_2051
	v_ashrrev_i32_e32 v39, 31, v38
	v_lshlrev_b64 v[36:37], 12, v[38:39]
	v_lshl_add_u64 v[34:35], s[6:7], 0, v[36:37]
	s_mov_b64 s[42:43], 0

.LBB0_2053:
	v_lshl_add_u64 v[34:35], v[34:35], 0, v[166:167]
	global_load_dwordx4 v[234:237], v[34:35], off
	global_load_dwordx4 v[238:241], v[34:35], off offset:16
	global_load_dwordx4 v[242:245], v[34:35], off offset:512
	global_load_dwordx4 v[246:249], v[34:35], off offset:528
	v_lshl_add_u64 v[36:37], s[88:89], 0, v[36:37]
	v_lshl_add_u64 v[36:37], v[36:37], 0, v[166:167]
	s_and_b64 vcc, exec, s[4:5]
	s_mov_b64 s[4:5], -1
	s_waitcnt vmcnt(3)
	v_pk_mul_f32 v[236:237], v[236:237], s[20:21] op_sel_hi:[1,0]
	v_pk_mul_f32 v[234:235], v[234:235], s[20:21] op_sel_hi:[1,0]
	v_pk_fma_f32 v[32:33], v[32:33], v[124:125], v[236:237]
	v_pk_fma_f32 v[30:31], v[30:31], v[122:123], v[234:235]
	global_store_dwordx4 v[36:37], v[30:33], off
	s_nop 0
	s_waitcnt vmcnt(3)
	v_pk_mul_f32 v[240:241], v[240:241], s[20:21] op_sel_hi:[1,0]
	v_pk_mul_f32 v[238:239], v[238:239], s[20:21] op_sel_hi:[1,0]
	v_pk_fma_f32 v[28:29], v[28:29], v[116:117], v[240:241]
	v_pk_fma_f32 v[26:27], v[26:27], v[114:115], v[238:239]
	global_store_dwordx4 v[36:37], v[26:29], off offset:16
	s_nop 0
	s_waitcnt vmcnt(3)
	v_pk_mul_f32 v[244:245], v[244:245], s[20:21] op_sel_hi:[1,0]
	v_pk_mul_f32 v[242:243], v[242:243], s[20:21] op_sel_hi:[1,0]
	v_pk_fma_f32 v[24:25], v[24:25], v[112:113], v[244:245]
	v_pk_fma_f32 v[22:23], v[22:23], v[110:111], v[242:243]
	global_store_dwordx4 v[36:37], v[22:25], off offset:512
	s_nop 0
	s_waitcnt vmcnt(3)
	v_pk_mul_f32 v[248:249], v[248:249], s[20:21] op_sel_hi:[1,0]
	v_pk_mul_f32 v[246:247], v[246:247], s[20:21] op_sel_hi:[1,0]
	v_add_u32_e32 v22, 0xb0, v164
	v_pk_fma_f32 v[18:19], v[18:19], v[106:107], v[246:247]
	v_pk_fma_f32 v[20:21], v[20:21], v[108:109], v[248:249]
	global_store_dwordx4 v[36:37], v[18:21], off offset:528
	s_cbranch_vccnz .LBB0_2055
	v_ashrrev_i32_e32 v23, 31, v22
	v_lshlrev_b64 v[20:21], 12, v[22:23]
	v_lshl_add_u64 v[18:19], s[6:7], 0, v[20:21]
	s_mov_b64 s[4:5], 0

.LBB0_2057:
	v_lshl_add_u64 v[18:19], v[18:19], 0, v[166:167]
	global_load_dwordx4 v[234:237], v[18:19], off
	global_load_dwordx4 v[238:241], v[18:19], off offset:16
	global_load_dwordx4 v[242:245], v[18:19], off offset:512
	global_load_dwordx4 v[246:249], v[18:19], off offset:528
	v_lshl_add_u64 v[20:21], s[88:89], 0, v[20:21]
	v_lshl_add_u64 v[20:21], v[20:21], 0, v[166:167]
	s_and_b64 vcc, exec, s[2:3]
	s_mov_b64 s[2:3], -1
	s_waitcnt vmcnt(3)
	v_pk_mul_f32 v[236:237], v[236:237], s[20:21] op_sel_hi:[1,0]
	v_pk_mul_f32 v[234:235], v[234:235], s[20:21] op_sel_hi:[1,0]
	v_pk_fma_f32 v[16:17], v[16:17], v[124:125], v[236:237]
	v_pk_fma_f32 v[14:15], v[14:15], v[122:123], v[234:235]
	global_store_dwordx4 v[20:21], v[14:17], off
	s_nop 0
	s_waitcnt vmcnt(3)
	v_pk_mul_f32 v[240:241], v[240:241], s[20:21] op_sel_hi:[1,0]
	v_pk_mul_f32 v[238:239], v[238:239], s[20:21] op_sel_hi:[1,0]
	v_pk_fma_f32 v[12:13], v[12:13], v[116:117], v[240:241]
	v_pk_fma_f32 v[10:11], v[10:11], v[114:115], v[238:239]
	global_store_dwordx4 v[20:21], v[10:13], off offset:16
	s_nop 0
	s_waitcnt vmcnt(3)
	v_pk_mul_f32 v[244:245], v[244:245], s[20:21] op_sel_hi:[1,0]
	v_pk_mul_f32 v[242:243], v[242:243], s[20:21] op_sel_hi:[1,0]
	v_pk_fma_f32 v[8:9], v[8:9], v[112:113], v[244:245]
	v_pk_fma_f32 v[6:7], v[6:7], v[110:111], v[242:243]
	global_store_dwordx4 v[20:21], v[6:9], off offset:512
	s_nop 0
	s_waitcnt vmcnt(3)
	v_pk_mul_f32 v[248:249], v[248:249], s[20:21] op_sel_hi:[1,0]
	v_pk_mul_f32 v[246:247], v[246:247], s[20:21] op_sel_hi:[1,0]
	v_pk_fma_f32 v[4:5], v[4:5], v[108:109], v[248:249]
	v_pk_fma_f32 v[2:3], v[2:3], v[106:107], v[246:247]
	global_store_dwordx4 v[20:21], v[2:5], off offset:528
	s_cbranch_vccnz .LBB0_2010
	s_andn2_b64 vcc, exec, s[10:11]
	s_cbranch_vccnz .LBB0_2009
	s_barrier
	s_branch .LBB0_2009
